# prompt attention K/V staging hand-written: row-contiguous loads, all issued up front
# baseline (speedup 1.0000x reference)
; #define LAS __attribute__((address_space(3)))
; __device__ __forceinline__ void unpack8(u32x4 u, float* f) { f[0] = bflo(u.x); f[1] = bfhi(u.x); f[2] = bflo(u.y); f[3] = bfhi(u.y); f[4] = bflo(u.z); f[5] = bfhi(u.z); f[6] = bflo(u.w); f[7] = bfhi(u.w); }
; __device__ __forceinline__ void attn_prompt_item(const Args& A, LAS unsigned char* lds, int tid, int lane, int wave, int b, int nb, int kvh) {
;     const bf16_t* Z = (const bf16_t*)(A.ws + WS_Z); bf16_t* MIX = (bf16_t*)(A.ws + WS_XN);
;     const float* ct = (const float*)(A.ws + WS_ROPE); const float* st = ct + 2056 * 8;
;     const int fr = lane & 15, q4 = lane >> 4;
;     for (int idx = tid; idx < 2048; idx += 512) {
;         const int key = idx & 255, ch = idx >> 8; const int pos = (nb - 1) * 128 + key;
;         float kf[8], vf[8];
;         if (pos >= 0) {
;             const size_t row = (size_t)b * SEQ + pos; const bf16_t* kp = Z + row * NZ + O_K + kvh * 64;
;             unpack8(*(const u32x4*)(kp + ch * 8), kf); unpack8(*(const u32x4*)(Z + row * NZ + O_V + kvh * 64 + ch * 8), vf);
;             if (ch < 2) { float pf[8]; unpack8(*(const u32x4*)(kp + (ch ^ 1) * 8), pf);
; #pragma unroll
;                 for (int i = 0; i < 8; ++i) { const float c = ct[pos * 8 + i], s = st[pos * 8 + i]; kf[i] = ch == 0 ? kf[i] * c - pf[i] * s : kf[i] * c + pf[i] * s; } }
;             if (nb == NB - 1 && key >= 128) {
; __global__ void __launch_bounds__(512, 2) hymba_fwd(Args A) {
;     ...
;         for (;;) {
;             if (tid == 0) *s_item = (int)atomicAdd(ctl + CW_WORK + 3, 1u);
;             __syncthreads();
;             const int r = *s_item;
;             __syncthreads();
;             if (r >= N_PA) break;
;             const int kvh = r & 1, nb = (r >> 1) & 15, b = r >> 5;
;             attn_prompt_item(A, lds, tid, lane, wave, b, nb, kvh);
.LBB0_294:
	s_or_b64 exec, exec, s[8:9]
	s_waitcnt lgkmcnt(0)
	s_barrier
	ds_read_b32 v0, v135
	s_mov_b64 s[8:9], -1
	s_waitcnt lgkmcnt(0)
	s_barrier
	v_cmp_lt_i32_e32 vcc, s55, v0
	v_readfirstlane_b32 s10, v0
	s_cbranch_vccnz .LBB0_289
	s_bfe_u32 s20, s10, 0x40001
	s_ashr_i32 s14, s10, 5
	s_lshl_b32 s22, s20, 7
	s_ashr_i32 s15, s14, 31
	s_and_b32 s21, s10, 1
	s_lshl_b64 s[10:11], s[14:15], 11
	v_add_u32_e32 v66, s22, v65
	v_lshl_add_u64 v[0:1], s[10:11], 0, v[66:67]
	v_mov_b64_e32 v[2:3], s[94:95]
	s_cmp_eq_u32 s20, 15
	v_mad_u64_u32 v[2:3], s[16:17], v0, s56, v[2:3]
	s_cselect_b64 s[12:13], -1, 0
	v_mad_i32_i24 v3, v1, s56, v3
	s_lshl_b32 s42, s21, 7
	v_lshl_add_u64 v[0:1], v[2:3], 0, s[42:43]
	s_mov_b64 s[16:17], 0x1500
	v_lshl_add_u64 v[22:23], v[0:1], 0, s[16:17]
	v_lshlrev_b32_e32 v0, 3, v66
	v_mov_b32_e32 v1, v67
	v_lshlrev_b64 v[2:3], 2, v[0:1]
	v_lshl_add_u64 v[24:25], s[88:89], 0, v[2:3]
	v_lshl_add_u64 v[26:27], s[90:91], 0, v[2:3]
	v_or_b32_e32 v2, 1, v0
	v_or_b32_e32 v0, 3, v0
	v_mov_b32_e32 v3, v67
	v_lshl_add_u64 v[30:31], v[0:1], 2, s[88:89]
	v_lshl_add_u32 v0, s14, 7, v65
	v_lshl_add_u64 v[28:29], v[2:3], 2, s[90:91]
	v_ashrrev_i32_e32 v1, 31, v0
	v_mad_u64_u32 v[2:3], s[16:17], v66, s56, 0
	v_mad_i64_i32 v[2:3], s[14:15], s14, v139, v[2:3]
	v_lshlrev_b64 v[0:1], 9, v[0:1]
	v_or_b32_e32 v2, s42, v2
	v_lshl_or_b32 v0, s21, 8, v0
	v_cmp_lt_i32_e64 s[8:9], -1, v66
	s_and_b64 s[12:13], s[12:13], s[40:41]
	v_lshl_add_u64 v[32:33], v[86:87], 0, v[2:3]
	v_lshl_add_u64 v[34:35], v[92:93], 0, v[0:1]
	s_mov_b64 s[14:15], 0
	v_mov_b32_e32 v9, v73
	v_mov_b32_e32 v42, v75
	v_mov_b32_e32 v43, v72
	v_mov_b32_e32 v44, v144
	s_add_i32 s23, s10, s22
	s_sub_i32 s23, s23, 0x80
	s_mul_i32 s16, s23, 0x1c00
	s_mul_hi_i32 s17, s23, 0x1c00
	s_add_u32 s16, s16, s94
	s_addc_u32 s17, s17, s95
	s_add_i32 s59, s42, 0x1500
	s_add_u32 s16, s16, s59
	s_addc_u32 s17, s17, 0
	s_sub_i32 s59, s22, 0x80
	s_lshl_b32 s59, s59, 5
	s_ashr_i32 s78, s59, 31
	s_add_u32 s18, s88, s59
	s_addc_u32 s19, s89, s78
	s_add_u32 s24, s18, 0x1000
	s_addc_u32 s25, s19, 0
	s_add_u32 s26, s90, s59
	s_addc_u32 s27, s91, s78
	s_add_u32 s28, s26, 0x1000
	s_addc_u32 s29, s27, 0
	s_mov_b32 s34, 0x03030303
	s_mov_b32 s35, 0x03030303
	s_lshl_b32 s59, s10, 5
	s_lshl_b32 s78, s21, 8
	s_add_i32 s59, s59, s78
	s_add_u32 s12, s86, 0x861a000
	s_addc_u32 s13, s87, 0
	s_add_u32 s12, s12, s59
	s_addc_u32 s13, s13, 0
	s_add_u32 s64, s12, 0x100000
	s_addc_u32 s65, s13, 0
	s_mov_b64 exec, -1
	v_lshrrev_b32_e32 v127, 3, v144
	v_and_b32_e32 v192, 7, v144
	v_mul_u32_u24_e32 v56, 0x1c00, v127
	v_lshl_add_u32 v56, v192, 4, v56
	v_add_u32_e32 v57, 0x70000, v56
	v_add_u32_e32 v58, 0xe0000, v56
	v_add_u32_e32 v59, 0x150000, v56
	v_xor_b32_e32 v60, 16, v56
	v_xor_b32_e32 v61, 16, v57
	v_xor_b32_e32 v62, 16, v58
	v_xor_b32_e32 v63, 16, v59
	v_lshlrev_b32_e32 v122, 5, v127
	v_mul_u32_u24_e32 v123, 0x90, v127
	v_lshl_add_u32 v123, v192, 4, v123
	v_mul_u32_u24_e32 v124, 0x1080, v192
	v_lshl_add_u32 v124, v127, 1, v124
	v_lshlrev_b32_e32 v125, 9, v127
	v_lshl_add_u32 v125, v192, 5, v125
	v_add_u32_e32 v193, 0x8000, v125
	v_cmp_eq_u32_e32 vcc, 0, v192
	v_mov_b32_e32 v126, 0x80000000
	s_nop 0
	v_cndmask_b32_e32 v126, 0, v126, vcc
	s_cmp_eq_u32 s20, 0
	s_cbranch_scc1 .Lpst_ld23
	global_load_dwordx4 v[0:3], v56, s[16:17]
	global_load_dwordx4 v[4:7], v56, s[16:17] offset:256
	s_mov_b64 exec, s[34:35]
	global_load_dwordx4 v[8:11], v60, s[16:17]
	global_load_dwordx4 v[12:15], v122, s[18:19]
	global_load_dwordx4 v[16:19], v122, s[18:19] offset:16
	global_load_dwordx4 v[20:23], v122, s[26:27]
	global_load_dwordx4 v[24:27], v122, s[26:27] offset:16
	s_mov_b64 exec, -1
	global_load_dwordx4 v[28:31], v57, s[16:17]
	global_load_dwordx4 v[32:35], v57, s[16:17] offset:256
	s_mov_b64 exec, s[34:35]
	global_load_dwordx4 v[36:39], v61, s[16:17]
	global_load_dwordx4 v[40:43], v122, s[18:19] offset:2048
	global_load_dwordx4 v[44:47], v122, s[18:19] offset:2064
	global_load_dwordx4 v[48:51], v122, s[26:27] offset:2048
	global_load_dwordx4 v[52:55], v122, s[26:27] offset:2064
	s_mov_b64 exec, -1
.Lpst_ld23:
	global_load_dwordx4 v[94:97], v58, s[16:17]
	global_load_dwordx4 v[98:101], v58, s[16:17] offset:256
	s_mov_b64 exec, s[34:35]
	global_load_dwordx4 v[102:105], v62, s[16:17]
	global_load_dwordx4 v[106:109], v122, s[24:25]
	global_load_dwordx4 v[110:113], v122, s[24:25] offset:16
	global_load_dwordx4 v[114:117], v122, s[28:29]
	global_load_dwordx4 v[118:121], v122, s[28:29] offset:16
	s_mov_b64 exec, -1
	global_load_dwordx4 v[148:151], v59, s[16:17]
	global_load_dwordx4 v[152:155], v59, s[16:17] offset:256
	s_mov_b64 exec, s[34:35]
	global_load_dwordx4 v[156:159], v63, s[16:17]
	global_load_dwordx4 v[160:163], v122, s[24:25] offset:2048
	global_load_dwordx4 v[164:167], v122, s[24:25] offset:2064
	global_load_dwordx4 v[168:171], v122, s[28:29] offset:2048
	global_load_dwordx4 v[172:175], v122, s[28:29] offset:2064
	s_mov_b64 exec, -1
	s_cmp_eq_u32 s20, 0
	s_cbranch_scc1 .Lpst_zero
; #define LAS __attribute__((address_space(3)))
; __device__ __forceinline__ unsigned f2bf(float f) { return pk2(f, 0.f) & 0xffffu; }
; __device__ __forceinline__ void unpack8(u32x4 u, float* f) { f[0] = bflo(u.x); f[1] = bfhi(u.x); f[2] = bflo(u.y); f[3] = bfhi(u.y); f[4] = bflo(u.z); f[5] = bfhi(u.z); f[6] = bflo(u.w); f[7] = bfhi(u.w); }
; __device__ __forceinline__ u32x4 pack8(const float* f) { u32x4 o; o.x = pk2(f[0], f[1]); o.y = pk2(f[2], f[3]); o.z = pk2(f[4], f[5]); o.w = pk2(f[6], f[7]); return o; }
; __device__ __forceinline__ void attn_prompt_item(const Args& A, LAS unsigned char* lds, int tid, int lane, int wave, int b, int nb, int kvh) {
;     ...
;         if (pos >= 0) {
;             const size_t row = (size_t)b * SEQ + pos; const bf16_t* kp = Z + row * NZ + O_K + kvh * 64;
;             unpack8(*(const u32x4*)(kp + ch * 8), kf); unpack8(*(const u32x4*)(Z + row * NZ + O_V + kvh * 64 + ch * 8), vf);
;             if (ch < 2) { float pf[8]; unpack8(*(const u32x4*)(kp + (ch ^ 1) * 8), pf);
; #pragma unroll
;                 for (int i = 0; i < 8; ++i) { const float c = ct[pos * 8 + i], s = st[pos * 8 + i]; kf[i] = ch == 0 ? kf[i] * c - pf[i] * s : kf[i] * c + pf[i] * s; } }
;             if (nb == NB - 1 && key >= 128) {
;                 float* ko = A.out + OUT_KP + ((size_t)(b * 128 + key - 128) * 2 + kvh) * 64 + ch * 8; float* vo = A.out + OUT_VP + ((size_t)(b * 128 + key - 128) * 2 + kvh) * 64 + ch * 8;
;                 *(f32x4*)ko = (f32x4){kf[0], kf[1], kf[2], kf[3]}; *(f32x4*)(ko + 4) = (f32x4){kf[4], kf[5], kf[6], kf[7]};
;                 *(f32x4*)vo = (f32x4){vf[0], vf[1], vf[2], vf[3]}; *(f32x4*)(vo + 4) = (f32x4){vf[4], vf[5], vf[6], vf[7]};
;             }
;         } else {
; #pragma unroll
;             for (int i = 0; i < 8; ++i) { kf[i] = 0.f; vf[i] = 0.f; }
;         }
;         *(LAS u32x4*)(lds + AT_K + key * 144 + ch * 16) = pack8(kf);
; #pragma unroll
;         for (int i = 0; i < 8; ++i) *(LAS unsigned short*)(lds + AT_V + (ch * 8 + i) * 528 + key * 2) = (unsigned short)f2bf(vf[i]);
	s_waitcnt vmcnt(21)
	v_lshlrev_b32_e32 v176, 16, v0
	v_and_b32_e32 v177, 0xffff0000, v0
	v_lshlrev_b32_e32 v178, 16, v1
	v_and_b32_e32 v179, 0xffff0000, v1
	v_lshlrev_b32_e32 v180, 16, v2
	v_and_b32_e32 v181, 0xffff0000, v2
	v_lshlrev_b32_e32 v182, 16, v3
	v_and_b32_e32 v183, 0xffff0000, v3
	s_mov_b64 exec, s[34:35]
	v_lshlrev_b32_e32 v192, 16, v8
	v_mul_f32_e32 v192, v20, v192
	v_xor_b32_e32 v192, v126, v192
	v_fma_f32 v176, v12, v176, v192
	v_and_b32_e32 v192, 0xffff0000, v8
	v_mul_f32_e32 v192, v21, v192
	v_xor_b32_e32 v192, v126, v192
	v_fma_f32 v177, v13, v177, v192
	v_lshlrev_b32_e32 v192, 16, v9
	v_mul_f32_e32 v192, v22, v192
	v_xor_b32_e32 v192, v126, v192
	v_fma_f32 v178, v14, v178, v192
	v_and_b32_e32 v192, 0xffff0000, v9
	v_mul_f32_e32 v192, v23, v192
	v_xor_b32_e32 v192, v126, v192
	v_fma_f32 v179, v15, v179, v192
	v_lshlrev_b32_e32 v192, 16, v10
	v_mul_f32_e32 v192, v24, v192
	v_xor_b32_e32 v192, v126, v192
	v_fma_f32 v180, v16, v180, v192
	v_and_b32_e32 v192, 0xffff0000, v10
	v_mul_f32_e32 v192, v25, v192
	v_xor_b32_e32 v192, v126, v192
	v_fma_f32 v181, v17, v181, v192
	v_lshlrev_b32_e32 v192, 16, v11
	v_mul_f32_e32 v192, v26, v192
	v_xor_b32_e32 v192, v126, v192
	v_fma_f32 v182, v18, v182, v192
	v_and_b32_e32 v192, 0xffff0000, v11
	v_mul_f32_e32 v192, v27, v192
	v_xor_b32_e32 v192, v126, v192
	v_fma_f32 v183, v19, v183, v192
	s_mov_b64 exec, -1
	v_cvt_pk_bf16_f32 v0, v176, v177
	v_cvt_pk_bf16_f32 v1, v178, v179
	v_cvt_pk_bf16_f32 v2, v180, v181
	v_cvt_pk_bf16_f32 v3, v182, v183
	ds_write_b128 v123, v[0:3]
	ds_write_b16 v124, v4 offset:36864
	ds_write_b16_d16_hi v124, v4 offset:37392
	ds_write_b16 v124, v5 offset:37920
	ds_write_b16_d16_hi v124, v5 offset:38448
	ds_write_b16 v124, v6 offset:38976
	ds_write_b16_d16_hi v124, v6 offset:39504
	ds_write_b16 v124, v7 offset:40032
	ds_write_b16_d16_hi v124, v7 offset:40560
	s_waitcnt vmcnt(14)
	v_lshlrev_b32_e32 v176, 16, v28
	v_and_b32_e32 v177, 0xffff0000, v28
	v_lshlrev_b32_e32 v178, 16, v29
	v_and_b32_e32 v179, 0xffff0000, v29
	v_lshlrev_b32_e32 v180, 16, v30
	v_and_b32_e32 v181, 0xffff0000, v30
	v_lshlrev_b32_e32 v182, 16, v31
	v_and_b32_e32 v183, 0xffff0000, v31
	s_mov_b64 exec, s[34:35]
	v_lshlrev_b32_e32 v192, 16, v36
	v_mul_f32_e32 v192, v48, v192
	v_xor_b32_e32 v192, v126, v192
	v_fma_f32 v176, v40, v176, v192
	v_and_b32_e32 v192, 0xffff0000, v36
	v_mul_f32_e32 v192, v49, v192
	v_xor_b32_e32 v192, v126, v192
	v_fma_f32 v177, v41, v177, v192
	v_lshlrev_b32_e32 v192, 16, v37
	v_mul_f32_e32 v192, v50, v192
	v_xor_b32_e32 v192, v126, v192
	v_fma_f32 v178, v42, v178, v192
	v_and_b32_e32 v192, 0xffff0000, v37
	v_mul_f32_e32 v192, v51, v192
	v_xor_b32_e32 v192, v126, v192
	v_fma_f32 v179, v43, v179, v192
	v_lshlrev_b32_e32 v192, 16, v38
	v_mul_f32_e32 v192, v52, v192
	v_xor_b32_e32 v192, v126, v192
	v_fma_f32 v180, v44, v180, v192
	v_and_b32_e32 v192, 0xffff0000, v38
	v_mul_f32_e32 v192, v53, v192
	v_xor_b32_e32 v192, v126, v192
	v_fma_f32 v181, v45, v181, v192
	v_lshlrev_b32_e32 v192, 16, v39
	v_mul_f32_e32 v192, v54, v192
	v_xor_b32_e32 v192, v126, v192
	v_fma_f32 v182, v46, v182, v192
	v_and_b32_e32 v192, 0xffff0000, v39
	v_mul_f32_e32 v192, v55, v192
	v_xor_b32_e32 v192, v126, v192
	v_fma_f32 v183, v47, v183, v192
	s_mov_b64 exec, -1
	v_cvt_pk_bf16_f32 v28, v176, v177
	v_cvt_pk_bf16_f32 v29, v178, v179
	v_cvt_pk_bf16_f32 v30, v180, v181
	v_cvt_pk_bf16_f32 v31, v182, v183
	ds_write_b128 v123, v[28:31] offset:9216
	ds_write_b16 v124, v32 offset:36992
	ds_write_b16_d16_hi v124, v32 offset:37520
	ds_write_b16 v124, v33 offset:38048
	ds_write_b16_d16_hi v124, v33 offset:38576
	ds_write_b16 v124, v34 offset:39104
	ds_write_b16_d16_hi v124, v34 offset:39632
	ds_write_b16 v124, v35 offset:40160
	ds_write_b16_d16_hi v124, v35 offset:40688
	s_branch .Lpst_p23
.Lpst_zero:
	v_mov_b32_e32 v196, 0
	v_mov_b32_e32 v197, 0
	v_mov_b32_e32 v198, 0
	v_mov_b32_e32 v199, 0
	ds_write_b128 v123, v[196:199]
	ds_write_b16 v124, v196 offset:36864
	ds_write_b16 v124, v196 offset:37392
	ds_write_b16 v124, v196 offset:37920
	ds_write_b16 v124, v196 offset:38448
	ds_write_b16 v124, v196 offset:38976
	ds_write_b16 v124, v196 offset:39504
	ds_write_b16 v124, v196 offset:40032
	ds_write_b16 v124, v196 offset:40560
	ds_write_b128 v123, v[196:199] offset:9216
	ds_write_b16 v124, v196 offset:36992
	ds_write_b16 v124, v196 offset:37520
	ds_write_b16 v124, v196 offset:38048
	ds_write_b16 v124, v196 offset:38576
	ds_write_b16 v124, v196 offset:39104
	ds_write_b16 v124, v196 offset:39632
	ds_write_b16 v124, v196 offset:40160
	ds_write_b16 v124, v196 offset:40688
; #define LAS __attribute__((address_space(3)))
; __device__ __forceinline__ unsigned f2bf(float f) { return pk2(f, 0.f) & 0xffffu; }
; __device__ __forceinline__ void unpack8(u32x4 u, float* f) { f[0] = bflo(u.x); f[1] = bfhi(u.x); f[2] = bflo(u.y); f[3] = bfhi(u.y); f[4] = bflo(u.z); f[5] = bfhi(u.z); f[6] = bflo(u.w); f[7] = bfhi(u.w); }
; __device__ __forceinline__ u32x4 pack8(const float* f) { u32x4 o; o.x = pk2(f[0], f[1]); o.y = pk2(f[2], f[3]); o.z = pk2(f[4], f[5]); o.w = pk2(f[6], f[7]); return o; }
; __device__ __forceinline__ void attn_prompt_item(const Args& A, LAS unsigned char* lds, int tid, int lane, int wave, int b, int nb, int kvh) {
;     ...
;         if (pos >= 0) {
;             const size_t row = (size_t)b * SEQ + pos; const bf16_t* kp = Z + row * NZ + O_K + kvh * 64;
;             unpack8(*(const u32x4*)(kp + ch * 8), kf); unpack8(*(const u32x4*)(Z + row * NZ + O_V + kvh * 64 + ch * 8), vf);
;             if (ch < 2) { float pf[8]; unpack8(*(const u32x4*)(kp + (ch ^ 1) * 8), pf);
; #pragma unroll
;                 for (int i = 0; i < 8; ++i) { const float c = ct[pos * 8 + i], s = st[pos * 8 + i]; kf[i] = ch == 0 ? kf[i] * c - pf[i] * s : kf[i] * c + pf[i] * s; } }
;             if (nb == NB - 1 && key >= 128) {
;                 float* ko = A.out + OUT_KP + ((size_t)(b * 128 + key - 128) * 2 + kvh) * 64 + ch * 8; float* vo = A.out + OUT_VP + ((size_t)(b * 128 + key - 128) * 2 + kvh) * 64 + ch * 8;
;                 *(f32x4*)ko = (f32x4){kf[0], kf[1], kf[2], kf[3]}; *(f32x4*)(ko + 4) = (f32x4){kf[4], kf[5], kf[6], kf[7]};
;                 *(f32x4*)vo = (f32x4){vf[0], vf[1], vf[2], vf[3]}; *(f32x4*)(vo + 4) = (f32x4){vf[4], vf[5], vf[6], vf[7]};
;             }
;         } else {
; #pragma unroll
;             for (int i = 0; i < 8; ++i) { kf[i] = 0.f; vf[i] = 0.f; }
;         }
;         *(LAS u32x4*)(lds + AT_K + key * 144 + ch * 16) = pack8(kf);
; #pragma unroll
;         for (int i = 0; i < 8; ++i) *(LAS unsigned short*)(lds + AT_V + (ch * 8 + i) * 528 + key * 2) = (unsigned short)f2bf(vf[i]);
.Lpst_p23:
	s_waitcnt vmcnt(7)
	v_lshlrev_b32_e32 v176, 16, v94
	v_and_b32_e32 v177, 0xffff0000, v94
	v_lshlrev_b32_e32 v178, 16, v95
	v_and_b32_e32 v179, 0xffff0000, v95
	v_lshlrev_b32_e32 v180, 16, v96
	v_and_b32_e32 v181, 0xffff0000, v96
	v_lshlrev_b32_e32 v182, 16, v97
	v_and_b32_e32 v183, 0xffff0000, v97
	s_mov_b64 exec, s[34:35]
	v_lshlrev_b32_e32 v192, 16, v102
	v_mul_f32_e32 v192, v114, v192
	v_xor_b32_e32 v192, v126, v192
	v_fma_f32 v176, v106, v176, v192
	v_and_b32_e32 v192, 0xffff0000, v102
	v_mul_f32_e32 v192, v115, v192
	v_xor_b32_e32 v192, v126, v192
	v_fma_f32 v177, v107, v177, v192
	v_lshlrev_b32_e32 v192, 16, v103
	v_mul_f32_e32 v192, v116, v192
	v_xor_b32_e32 v192, v126, v192
	v_fma_f32 v178, v108, v178, v192
	v_and_b32_e32 v192, 0xffff0000, v103
	v_mul_f32_e32 v192, v117, v192
	v_xor_b32_e32 v192, v126, v192
	v_fma_f32 v179, v109, v179, v192
	v_lshlrev_b32_e32 v192, 16, v104
	v_mul_f32_e32 v192, v118, v192
	v_xor_b32_e32 v192, v126, v192
	v_fma_f32 v180, v110, v180, v192
	v_and_b32_e32 v192, 0xffff0000, v104
	v_mul_f32_e32 v192, v119, v192
	v_xor_b32_e32 v192, v126, v192
	v_fma_f32 v181, v111, v181, v192
	v_lshlrev_b32_e32 v192, 16, v105
	v_mul_f32_e32 v192, v120, v192
	v_xor_b32_e32 v192, v126, v192
	v_fma_f32 v182, v112, v182, v192
	v_and_b32_e32 v192, 0xffff0000, v105
	v_mul_f32_e32 v192, v121, v192
	v_xor_b32_e32 v192, v126, v192
	v_fma_f32 v183, v113, v183, v192
	s_mov_b64 exec, -1
	v_cvt_pk_bf16_f32 v94, v176, v177
	v_cvt_pk_bf16_f32 v95, v178, v179
	v_cvt_pk_bf16_f32 v96, v180, v181
	v_cvt_pk_bf16_f32 v97, v182, v183
	ds_write_b128 v123, v[94:97] offset:18432
	ds_write_b16 v124, v98 offset:37120
	ds_write_b16_d16_hi v124, v98 offset:37648
	ds_write_b16 v124, v99 offset:38176
	ds_write_b16_d16_hi v124, v99 offset:38704
	ds_write_b16 v124, v100 offset:39232
	ds_write_b16_d16_hi v124, v100 offset:39760
	ds_write_b16 v124, v101 offset:40288
	ds_write_b16_d16_hi v124, v101 offset:40816
	s_cmp_eq_u32 s20, 15
	s_cbranch_scc0 .Lpst_noout2
	v_lshlrev_b32_e32 v184, 16, v98
	v_and_b32_e32 v185, 0xffff0000, v98
	v_lshlrev_b32_e32 v186, 16, v99
	v_and_b32_e32 v187, 0xffff0000, v99
	v_lshlrev_b32_e32 v188, 16, v100
	v_and_b32_e32 v189, 0xffff0000, v100
	v_lshlrev_b32_e32 v190, 16, v101
	v_and_b32_e32 v191, 0xffff0000, v101
	global_store_dwordx4 v125, v[176:179], s[12:13]
	global_store_dwordx4 v125, v[180:183], s[12:13] offset:16
	global_store_dwordx4 v125, v[184:187], s[64:65]
	global_store_dwordx4 v125, v[188:191], s[64:65] offset:16
.Lpst_noout2:
	s_waitcnt vmcnt(0)
	v_lshlrev_b32_e32 v176, 16, v148
	v_and_b32_e32 v177, 0xffff0000, v148
	v_lshlrev_b32_e32 v178, 16, v149
	v_and_b32_e32 v179, 0xffff0000, v149
	v_lshlrev_b32_e32 v180, 16, v150
	v_and_b32_e32 v181, 0xffff0000, v150
	v_lshlrev_b32_e32 v182, 16, v151
	v_and_b32_e32 v183, 0xffff0000, v151
	s_mov_b64 exec, s[34:35]
	v_lshlrev_b32_e32 v192, 16, v156
	v_mul_f32_e32 v192, v168, v192
	v_xor_b32_e32 v192, v126, v192
	v_fma_f32 v176, v160, v176, v192
	v_and_b32_e32 v192, 0xffff0000, v156
	v_mul_f32_e32 v192, v169, v192
	v_xor_b32_e32 v192, v126, v192
	v_fma_f32 v177, v161, v177, v192
	v_lshlrev_b32_e32 v192, 16, v157
	v_mul_f32_e32 v192, v170, v192
	v_xor_b32_e32 v192, v126, v192
	v_fma_f32 v178, v162, v178, v192
	v_and_b32_e32 v192, 0xffff0000, v157
	v_mul_f32_e32 v192, v171, v192
	v_xor_b32_e32 v192, v126, v192
	v_fma_f32 v179, v163, v179, v192
	v_lshlrev_b32_e32 v192, 16, v158
	v_mul_f32_e32 v192, v172, v192
	v_xor_b32_e32 v192, v126, v192
	v_fma_f32 v180, v164, v180, v192
	v_and_b32_e32 v192, 0xffff0000, v158
	v_mul_f32_e32 v192, v173, v192
	v_xor_b32_e32 v192, v126, v192
	v_fma_f32 v181, v165, v181, v192
	v_lshlrev_b32_e32 v192, 16, v159
	v_mul_f32_e32 v192, v174, v192
	v_xor_b32_e32 v192, v126, v192
	v_fma_f32 v182, v166, v182, v192
	v_and_b32_e32 v192, 0xffff0000, v159
	v_mul_f32_e32 v192, v175, v192
	v_xor_b32_e32 v192, v126, v192
	v_fma_f32 v183, v167, v183, v192
	s_mov_b64 exec, -1
	v_cvt_pk_bf16_f32 v148, v176, v177
	v_cvt_pk_bf16_f32 v149, v178, v179
	v_cvt_pk_bf16_f32 v150, v180, v181
	v_cvt_pk_bf16_f32 v151, v182, v183
	ds_write_b128 v123, v[148:151] offset:27648
	ds_write_b16 v124, v152 offset:37248
	ds_write_b16_d16_hi v124, v152 offset:37776
	ds_write_b16 v124, v153 offset:38304
	ds_write_b16_d16_hi v124, v153 offset:38832
	ds_write_b16 v124, v154 offset:39360
	ds_write_b16_d16_hi v124, v154 offset:39888
	ds_write_b16 v124, v155 offset:40416
	ds_write_b16_d16_hi v124, v155 offset:40944
	s_cmp_eq_u32 s20, 15
	s_cbranch_scc0 .Lpst_noout3
	v_lshlrev_b32_e32 v184, 16, v152
	v_and_b32_e32 v185, 0xffff0000, v152
	v_lshlrev_b32_e32 v186, 16, v153
	v_and_b32_e32 v187, 0xffff0000, v153
	v_lshlrev_b32_e32 v188, 16, v154
	v_and_b32_e32 v189, 0xffff0000, v154
	v_lshlrev_b32_e32 v190, 16, v155
	v_and_b32_e32 v191, 0xffff0000, v155
	global_store_dwordx4 v193, v[176:179], s[12:13]
	global_store_dwordx4 v193, v[180:183], s[12:13] offset:16
	global_store_dwordx4 v193, v[184:187], s[64:65]
	global_store_dwordx4 v193, v[188:191], s[64:65] offset:16
; #define LAS __attribute__((address_space(3)))
; __device__ __forceinline__ void unpack8(u32x4 u, float* f) { f[0] = bflo(u.x); f[1] = bfhi(u.x); f[2] = bflo(u.y); f[3] = bfhi(u.y); f[4] = bflo(u.z); f[5] = bfhi(u.z); f[6] = bflo(u.w); f[7] = bfhi(u.w); }
; __device__ __forceinline__ void attn_prompt_item(const Args& A, LAS unsigned char* lds, int tid, int lane, int wave, int b, int nb, int kvh) {
;     ...
;     __syncthreads();
;     LAS unsigned char* Pw = lds + AT_P + wave * 2304;
;     for (int task = wave; task < 16; task += 8) {
;         const int g = task >> 2, tt = task & 3, hq = kvh * 4 + g;
;         const float sink = A.sinks[hq] * 1.4426950408889634f;
;         bf16x8 Qf[2][2];
; #pragma unroll
;         for (int mt = 0; mt < 2; ++mt)
; #pragma unroll
;             for (int ks = 0; ks < 2; ++ks) {
;                 const int tq = tt * 32 + mt * 16 + fr; const int pos = nb * 128 + tq; const size_t row = (size_t)b * SEQ + pos;
;                 const bf16_t* qp = Z + row * NZ + O_Q + hq * 64; const int d0 = ks * 32 + q4 * 8;
;                 float qf[8]; unpack8(*(const u32x4*)(qp + d0), qf);
;                 if (ks == 0 && q4 < 2) { float pf[8]; unpack8(*(const u32x4*)(qp + (d0 ^ 8)), pf);
; #pragma unroll
;                     for (int i = 0; i < 8; ++i) { const float c = ct[pos * 8 + i], s = st[pos * 8 + i]; qf[i] = q4 == 0 ? qf[i] * c - pf[i] * s : qf[i] * c + pf[i] * s; } }
; #pragma unroll
;                 for (int i = 0; i < 8; ++i) qf[i] *= 0.18033688011112042f;
;                 Qf[mt][ks] = __builtin_bit_cast(bf16x8, pack8(qf));
;             }
;         float mrow[2][4], lrow[2][4]; f32x4 O[2][4];
; #pragma unroll
;         for (int mt = 0; mt < 2; ++mt) {
; #pragma unroll
;             for (int j = 0; j < 4; ++j) { mrow[mt][j] = sink; lrow[mt][j] = 1.f; }
; #pragma unroll
;             for (int dt = 0; dt < 4; ++dt) O[mt][dt] = (f32x4){0.f, 0.f, 0.f, 0.f};
;         }
;         unsigned short gts[2][4][4];
; #pragma unroll
;         for (int mt = 0; mt < 2; ++mt)
; #pragma unroll
;             for (int j = 0; j < 4; ++j) { const size_t row = (size_t)b * SEQ + nb * 128 + tt * 32 + mt * 16 + q4 * 4 + j;
; #pragma unroll
;                 for (int dt = 0; dt < 4; ++dt) gts[mt][j][dt] = Z[row * NZ + O_GA + hq * 64 + dt * 16 + fr]; }
;         int kc_lo = tt < 2 ? 0 : 1; const int kc_hi = kc_lo + 3; if (nb == 0 && kc_lo < 2) kc_lo = 2;
.Lpst_noout3:
.LBB0_305:
	s_mov_b64 exec, -1
	s_andn2_b64 vcc, exec, s[44:45]
	s_waitcnt lgkmcnt(0)
	s_barrier
	s_cbranch_vccnz .LBB0_288
	v_or_b32_e32 v4, s22, v71
	v_or_b32_e32 v2, s10, v4
	v_mov_b64_e32 v[0:1], s[94:95]
	v_mad_u64_u32 v[2:3], s[8:9], v2, s56, v[0:1]
	v_mad_i32_i24 v3, s11, v141, v3
	v_lshlrev_b32_e32 v66, 5, v4
	v_or_b32_e32 v4, 16, v4
	v_lshl_add_u64 v[94:95], v[2:3], 0, s[46:47]
	v_or_b32_e32 v2, s10, v4
	v_mad_u64_u32 v[2:3], s[8:9], v2, s56, v[0:1]
	v_lshl_add_u64 v[96:97], s[88:89], 0, v[66:67]
	v_lshl_add_u64 v[98:99], s[90:91], 0, v[66:67]
	v_mad_i32_i24 v3, s11, v141, v3
	v_lshlrev_b32_e32 v66, 5, v4
	s_or_b32 s12, s10, s22
	v_lshl_add_u64 v[100:101], v[2:3], 0, s[46:47]
	v_or_b32_e32 v2, 4, v66
	v_mov_b32_e32 v3, v67
	v_lshl_add_u64 v[106:107], s[90:91], 0, v[2:3]
	v_or_b32_e32 v2, s12, v68
	v_mad_u64_u32 v[0:1], s[8:9], v2, s56, v[0:1]
	v_mad_i32_i24 v1, s11, v141, v1
	v_lshlrev_b32_e32 v110, 1, v132
	v_mov_b32_e32 v111, v67
	v_lshl_add_u64 v[0:1], v[0:1], 0, v[110:111]
	s_mov_b64 s[8:9], 0x1700
	v_lshl_add_u64 v[112:113], v[0:1], 0, s[8:9]
	s_mov_b64 s[8:9], 0x3300
	v_lshl_add_u64 v[114:115], v[0:1], 0, s[8:9]
	s_mov_b64 s[8:9], 0x4f00
	v_lshl_add_u64 v[116:117], v[0:1], 0, s[8:9]
	s_mov_b64 s[8:9], 0x6b00
	v_lshl_add_u64 v[118:119], v[0:1], 0, s[8:9]
	s_mov_b64 s[8:9], 0x1d700
	v_lshl_add_u64 v[120:121], v[0:1], 0, s[8:9]
	s_mov_b64 s[8:9], 0x1f300
	v_lshl_add_u64 v[122:123], v[0:1], 0, s[8:9]
	s_mov_b64 s[8:9], 0x20f00
	v_lshl_add_u64 v[124:125], v[0:1], 0, s[8:9]
	s_mov_b64 s[8:9], 0x22b00
	v_lshl_add_u64 v[126:127], v[0:1], 0, s[8:9]
	v_mov_b32_e32 v1, s11
	v_or_b32_e32 v0, s12, v70
	s_lshl_b32 s59, s21, 2
	v_lshlrev_b64 v[150:151], 11, v[0:1]
	v_or_b32_e32 v0, s12, v74
	s_cmp_lg_u32 s20, 0
	v_lshlrev_b64 v[152:153], 11, v[0:1]
	v_or_b32_e32 v0, s12, v76
	s_cselect_b32 s64, s52, 2
	v_lshlrev_b64 v[154:155], 11, v[0:1]
	v_or_b32_e32 v0, s12, v78
	v_lshlrev_b64 v[156:157], 11, v[0:1]
	v_or_b32_e32 v0, s12, v80
	s_lshl_b32 s8, s64, 7
	v_lshlrev_b64 v[158:159], 11, v[0:1]
	v_or_b32_e32 v0, s12, v82
	v_add_u32_e32 v147, s8, v77
	v_add_u32_e32 v176, s8, v79
	s_lshl_b32 s8, s64, 6
	v_lshl_add_u64 v[102:103], s[88:89], 0, v[66:67]
	v_lshl_add_u64 v[104:105], s[90:91], 0, v[66:67]
	v_or_b32_e32 v66, 12, v66
	v_mov_b32_e32 v3, s11
	v_lshlrev_b64 v[160:161], 11, v[0:1]
	v_or_b32_e32 v0, s12, v84
	v_subrev_u32_e32 v177, s8, v81
	s_mul_i32 s8, s64, 0x2400
	v_lshl_add_u64 v[108:109], s[88:89], 0, v[66:67]
	v_lshlrev_b64 v[148:149], 11, v[2:3]
	v_lshlrev_b64 v[162:163], 11, v[0:1]
	v_add_u32_e32 v178, s8, v83
	v_readlane_b32 s65, v249, 3
